# attention: LDS stage writes of the prefetched K/V tile issued right after the barrier that frees the stage (top of trip / after mid barrier) instead of before the next barrier (on top of nop-fill + K
# speedup vs baseline: 1.0034x; 1.0034x over previous
; DI void phase_attn(const Params& p, int hf, bool skipctx, char* smem, int& rot) {
;     ...
;           for (int ks = 0; ks < 6; ++ks) kf[kb][ks] = *(const bf16x8*)(sk + (kb * 32 + r) * KROW + (ks * 16 + h * 8) * 2);
;     ...
;     for (int kt = 0; kt < nkt; kt += 2) {
;       if (kt + 2 < nkt) ATT_LOAD(ak0, ak1, ak2, av0, av1, kt + 2);
;       compute(0, 0); compute(0, 1);
;       ATT_WRITE(bk0, bk1, bk2, bv0, bv1, 1);
.LBB0_795:
	s_waitcnt vmcnt(0)
	ds_write_b128 v176, v[112:115] offset:43520
	ds_write_b128 v177, v[108:111] offset:43520
	ds_write_b128 v178, v[116:119] offset:43520
	ds_write2_b64 v186, v[120:121], v[122:123] offset1:1
	ds_write2_b64 v187, v[124:125], v[126:127] offset1:1
	ds_read_b128 v[32:35], v190
	ds_read_b128 v[128:131], v190 offset:32
	ds_read_b128 v[132:135], v190 offset:64
	ds_read_b128 v[136:139], v190 offset:96
	ds_read_b128 v[140:143], v190 offset:128
	ds_read_b128 v[144:147], v190 offset:160
	ds_read_b128 v[36:39], v190 offset:6656
	ds_read_b128 v[148:151], v190 offset:6688
	ds_read_b128 v[152:155], v190 offset:6720
	ds_read_b128 v[156:159], v190 offset:6752
	ds_read_b128 v[214:217], v190 offset:6784
	ds_read_b128 v[234:237], v190 offset:6816
	s_add_i32 s15, s4, 2
	s_cmp_lt_u32 s15, s13
	s_cselect_b64 s[36:37], -1, 0
	s_cmp_ge_u32 s15, s13
	s_cselect_b64 s[26:27], -1, 0
	s_and_b64 vcc, exec, s[26:27]
	s_cbranch_vccnz .LBB0_797
	v_lshl_add_u64 v[200:201], s[94:95], 0, v[174:175]
	v_add_co_u32_e32 v200, vcc, 0x18b28000, v200
	v_lshl_add_u64 v[202:203], s[94:95], 0, v[172:173]
	s_nop 0
	v_addc_co_u32_e32 v201, vcc, 0, v201, vcc
	v_add_co_u32_e32 v202, vcc, 0x18b28000, v202
	s_nop 1
	v_addc_co_u32_e32 v203, vcc, 0, v203, vcc
	global_load_dwordx4 v[76:79], v[200:201], off
	global_load_dwordx4 v[80:83], v[202:203], off
	v_lshl_add_u64 v[200:201], s[94:95], 0, v[170:171]
	v_add_co_u32_e32 v200, vcc, 0x18b28000, v200
	v_lshl_add_u64 v[202:203], s[94:95], 0, v[166:167]
	s_nop 0
	v_addc_co_u32_e32 v201, vcc, 0, v201, vcc
	global_load_dwordx4 v[84:87], v[200:201], off
	global_load_dwordx4 v[92:95], v[202:203], off offset:-256
	v_lshl_add_u64 v[200:201], s[94:95], 0, v[168:169]
	global_load_dwordx4 v[104:107], v[200:201], off offset:-256

; #define MFMA(a, b, c) __builtin_amdgcn_mfma_f32_32x32x16_bf16((a), (b), (c), 0, 0, 0)
; DI float fexp2(float x) { return __builtin_amdgcn_exp2f(x); }
; DI void phase_attn(const Params& p, int hf, bool skipctx, char* smem, int& rot) {
;     ...
;       float ps = 0.f;
; #pragma unroll
;       for (int kb = 0; kb < 2; ++kb)
; #pragma unroll
;         for (int i = 0; i < 16; ++i) { const float e = fexp2(st[kb][i] - m_run); st[kb][i] = e; ps += e; }
;       l_run += ps;
; #pragma unroll
;       for (int kb = 0; kb < 2; ++kb)
; #pragma unroll
;         for (int s2 = 0; s2 < 2; ++s2) {
;           const bf16x8 pb = pack8(st[kb][8 * s2 + 0], st[kb][8 * s2 + 1], st[kb][8 * s2 + 2], st[kb][8 * s2 + 3], st[kb][8 * s2 + 4], st[kb][8 * s2 + 5], st[kb][8 * s2 + 6], st[kb][8 * s2 + 7]);
; #pragma unroll
;           for (int dvb = 0; dvb < 2; ++dvb) o[dvb] = MFMA(vf[kb][s2][dvb], pb, o[dvb]);
;         }
;     ...
;     for (int kt = 0; kt < nkt; kt += 2) {
;       if (kt + 2 < nkt) ATT_LOAD(ak0, ak1, ak2, av0, av1, kt + 2);
;       compute(0, 0); compute(0, 1);
;       ATT_WRITE(bk0, bk1, bk2, bv0, bv1, 1);
;       __syncthreads();
;       if (kt + 3 < nkt) ATT_LOAD(bk0, bk1, bk2, bv0, bv1, kt + 3);
;       compute(1, 0); compute(1, 1);
;       if (kt + 2 < nkt) ATT_WRITE(ak0, ak1, ak2, av0, av1, 0);
.LBB0_801:
	v_sub_f32_e32 v48, v48, v212
	v_sub_f32_e32 v49, v49, v212
	v_sub_f32_e32 v50, v50, v212
	v_sub_f32_e32 v51, v51, v212
	v_sub_f32_e32 v52, v52, v212
	v_sub_f32_e32 v53, v53, v212
	v_sub_f32_e32 v54, v54, v212
	v_sub_f32_e32 v55, v55, v212
	v_exp_f32_e32 v48, v48
	v_exp_f32_e32 v49, v49
	v_exp_f32_e32 v50, v50
	v_exp_f32_e32 v51, v51
	v_exp_f32_e32 v52, v52
	v_exp_f32_e32 v53, v53
	v_exp_f32_e32 v54, v54
	v_exp_f32_e32 v55, v55
	v_cvt_pk_bf16_f32 v214, v48, v49
	v_cvt_pk_bf16_f32 v215, v50, v51
	v_cvt_pk_bf16_f32 v216, v52, v53
	v_cvt_pk_bf16_f32 v217, v54, v55
	v_sub_f32_e32 v56, v56, v212
	v_sub_f32_e32 v57, v57, v212
	s_waitcnt lgkmcnt(7)
	v_mfma_f32_32x32x16_bf16 v[16:31], v[156:159], v[214:217], v[16:31]
	v_sub_f32_e32 v58, v58, v212
	v_sub_f32_e32 v59, v59, v212
	v_sub_f32_e32 v60, v60, v212
	v_sub_f32_e32 v61, v61, v212
	v_sub_f32_e32 v62, v62, v212
	v_sub_f32_e32 v63, v63, v212
	v_exp_f32_e32 v56, v56
	s_waitcnt lgkmcnt(5)
	v_mfma_f32_32x32x16_bf16 v[0:15], v[152:155], v[214:217], v[0:15]
	v_exp_f32_e32 v57, v57
	v_exp_f32_e32 v58, v58
	v_exp_f32_e32 v59, v59
	v_exp_f32_e32 v60, v60
	v_exp_f32_e32 v61, v61
	v_exp_f32_e32 v62, v62
	v_exp_f32_e32 v63, v63
	v_cvt_pk_bf16_f32 v152, v56, v57
	v_cvt_pk_bf16_f32 v153, v58, v59
	v_cvt_pk_bf16_f32 v154, v60, v61
	v_cvt_pk_bf16_f32 v155, v62, v63
	v_sub_f32_e32 v32, v32, v212
	v_sub_f32_e32 v33, v33, v212
	v_mfma_f32_32x32x16_bf16 v[16:31], v[148:151], v[152:155], v[16:31]
	v_sub_f32_e32 v34, v34, v212
	v_sub_f32_e32 v35, v35, v212
	v_sub_f32_e32 v36, v36, v212
	v_sub_f32_e32 v37, v37, v212
	v_sub_f32_e32 v38, v38, v212
	v_sub_f32_e32 v39, v39, v212
	v_exp_f32_e32 v32, v32
	s_waitcnt lgkmcnt(4)
	v_mfma_f32_32x32x16_bf16 v[0:15], v[144:147], v[152:155], v[0:15]
	v_exp_f32_e32 v33, v33
	v_exp_f32_e32 v34, v34
	v_exp_f32_e32 v35, v35
	v_exp_f32_e32 v36, v36
	v_exp_f32_e32 v37, v37
	v_exp_f32_e32 v38, v38
	v_exp_f32_e32 v39, v39
	v_cvt_pk_bf16_f32 v144, v32, v33
	v_cvt_pk_bf16_f32 v145, v34, v35
	v_cvt_pk_bf16_f32 v146, v36, v37
	v_cvt_pk_bf16_f32 v147, v38, v39
	v_sub_f32_e32 v40, v40, v212
	v_sub_f32_e32 v41, v41, v212
	s_waitcnt lgkmcnt(3)
	v_mfma_f32_32x32x16_bf16 v[16:31], v[140:143], v[144:147], v[16:31]
	v_sub_f32_e32 v42, v42, v212
	v_sub_f32_e32 v43, v43, v212
	v_sub_f32_e32 v44, v44, v212
	v_sub_f32_e32 v45, v45, v212
	v_sub_f32_e32 v46, v46, v212
	v_sub_f32_e32 v47, v47, v212
	v_exp_f32_e32 v40, v40
	s_waitcnt lgkmcnt(2)
	v_mfma_f32_32x32x16_bf16 v[0:15], v[136:139], v[144:147], v[0:15]
	v_exp_f32_e32 v41, v41
	v_exp_f32_e32 v42, v42
	v_exp_f32_e32 v43, v43
	v_exp_f32_e32 v44, v44
	v_exp_f32_e32 v45, v45
	v_exp_f32_e32 v46, v46
	v_exp_f32_e32 v47, v47
	v_cvt_pk_bf16_f32 v136, v40, v41
	v_cvt_pk_bf16_f32 v137, v42, v43
	v_cvt_pk_bf16_f32 v138, v44, v45
	v_cvt_pk_bf16_f32 v139, v46, v47
	s_add_i32 s4, s4, 3
	s_waitcnt lgkmcnt(1)
	v_mfma_f32_32x32x16_bf16 v[16:31], v[128:131], v[136:139], v[16:31]
	s_waitcnt lgkmcnt(0)
	s_barrier
	v_mfma_f32_32x32x16_bf16 v[0:15], v[132:135], v[136:139], v[0:15]
	s_andn2_b64 vcc, exec, s[36:37]
	s_cbranch_vccnz .Lattn0_wa_skip
	s_waitcnt vmcnt(0)
	ds_write_b128 v176, v[76:79]
	ds_write_b128 v177, v[80:83]
	ds_write_b128 v178, v[84:87]
	ds_write2_b64 v179, v[92:93], v[94:95] offset1:1
	ds_write2_b64 v180, v[104:105], v[106:107] offset1:1
.Lattn0_wa_skip:
	ds_read_b128 v[238:241], v190 offset:43520
	ds_read_b128 v[128:131], v190 offset:43552
	ds_read_b128 v[132:135], v190 offset:43584
	ds_read_b128 v[136:139], v190 offset:43616
	ds_read_b128 v[140:143], v190 offset:43648
	ds_read_b128 v[144:147], v190 offset:43680
	ds_read_b128 v[242:245], v190 offset:50176
	ds_read_b128 v[148:151], v190 offset:50208
	ds_read_b128 v[152:155], v190 offset:50240
	ds_read_b128 v[156:159], v190 offset:50272
	ds_read_b128 v[214:217], v190 offset:50304
	ds_read_b128 v[234:237], v190 offset:50336
	s_cmp_ge_u32 s4, s13
	s_cbranch_scc1 .LBB0_803
	v_lshl_add_u64 v[108:109], s[94:95], 0, v[174:175]
	v_add_co_u32_e32 v108, vcc, 0x18b2e000, v108
	v_lshl_add_u64 v[110:111], s[94:95], 0, v[172:173]
	s_nop 0
	v_addc_co_u32_e32 v109, vcc, 0, v109, vcc
	v_add_co_u32_e32 v110, vcc, 0x18b2e000, v110
	v_lshl_add_u64 v[116:117], s[94:95], 0, v[170:171]
	s_nop 0
	v_addc_co_u32_e32 v111, vcc, 0, v111, vcc
	v_add_co_u32_e32 v116, vcc, 0x18b2e000, v116
	v_lshl_add_u64 v[120:121], s[94:95], 0, v[166:167]
	s_nop 0
	v_addc_co_u32_e32 v117, vcc, 0, v117, vcc
	v_lshl_add_u64 v[124:125], s[94:95], 0, v[168:169]
	global_load_dwordx4 v[112:115], v[108:109], off
	s_nop 0
	global_load_dwordx4 v[108:111], v[110:111], off
	s_nop 0
	global_load_dwordx4 v[116:119], v[116:117], off
	s_nop 0
	global_load_dwordx4 v[120:123], v[120:121], off
	s_nop 0
	global_load_dwordx4 v[124:127], v[124:125], off

; #define MFMA(a, b, c) __builtin_amdgcn_mfma_f32_32x32x16_bf16((a), (b), (c), 0, 0, 0)
; DI float fexp2(float x) { return __builtin_amdgcn_exp2f(x); }
; DI void phase_attn(const Params& p, int hf, bool skipctx, char* smem, int& rot) {
;     ...
;       float ps = 0.f;
; #pragma unroll
;       for (int kb = 0; kb < 2; ++kb)
; #pragma unroll
;         for (int i = 0; i < 16; ++i) { const float e = fexp2(st[kb][i] - m_run); st[kb][i] = e; ps += e; }
;       l_run += ps;
; #pragma unroll
;       for (int kb = 0; kb < 2; ++kb)
; #pragma unroll
;         for (int s2 = 0; s2 < 2; ++s2) {
;           const bf16x8 pb = pack8(st[kb][8 * s2 + 0], st[kb][8 * s2 + 1], st[kb][8 * s2 + 2], st[kb][8 * s2 + 3], st[kb][8 * s2 + 4], st[kb][8 * s2 + 5], st[kb][8 * s2 + 6], st[kb][8 * s2 + 7]);
; #pragma unroll
;           for (int dvb = 0; dvb < 2; ++dvb) o[dvb] = MFMA(vf[kb][s2][dvb], pb, o[dvb]);
;         }
;     ...
;       compute(1, 0); compute(1, 1);
;       if (kt + 2 < nkt) ATT_WRITE(ak0, ak1, ak2, av0, av1, 0);
.LBB0_807:
	v_sub_f32_e32 v48, v48, v212
	v_sub_f32_e32 v49, v49, v212
	v_sub_f32_e32 v50, v50, v212
	v_sub_f32_e32 v51, v51, v212
	v_sub_f32_e32 v52, v52, v212
	v_sub_f32_e32 v53, v53, v212
	v_sub_f32_e32 v54, v54, v212
	v_sub_f32_e32 v55, v55, v212
	v_exp_f32_e32 v48, v48
	v_exp_f32_e32 v49, v49
	v_exp_f32_e32 v50, v50
	v_exp_f32_e32 v51, v51
	v_exp_f32_e32 v52, v52
	v_exp_f32_e32 v53, v53
	v_exp_f32_e32 v54, v54
	v_exp_f32_e32 v55, v55
	v_cvt_pk_bf16_f32 v214, v48, v49
	v_cvt_pk_bf16_f32 v215, v50, v51
	v_cvt_pk_bf16_f32 v216, v52, v53
	v_cvt_pk_bf16_f32 v217, v54, v55
	v_sub_f32_e32 v56, v56, v212
	v_sub_f32_e32 v57, v57, v212
	s_waitcnt lgkmcnt(6)
	v_mfma_f32_32x32x16_bf16 v[16:31], v[156:159], v[214:217], v[16:31]
	v_sub_f32_e32 v58, v58, v212
	v_sub_f32_e32 v59, v59, v212
	v_sub_f32_e32 v60, v60, v212
	v_sub_f32_e32 v61, v61, v212
	v_sub_f32_e32 v62, v62, v212
	v_sub_f32_e32 v63, v63, v212
	v_exp_f32_e32 v56, v56
	v_mfma_f32_32x32x16_bf16 v[0:15], v[152:155], v[214:217], v[0:15]
	v_exp_f32_e32 v57, v57
	v_exp_f32_e32 v58, v58
	v_exp_f32_e32 v59, v59
	v_exp_f32_e32 v60, v60
	v_exp_f32_e32 v61, v61
	v_exp_f32_e32 v62, v62
	v_exp_f32_e32 v63, v63
	v_cvt_pk_bf16_f32 v152, v56, v57
	v_cvt_pk_bf16_f32 v153, v58, v59
	v_cvt_pk_bf16_f32 v154, v60, v61
	v_cvt_pk_bf16_f32 v155, v62, v63
	v_sub_f32_e32 v32, v32, v212
	v_sub_f32_e32 v33, v33, v212
	s_waitcnt lgkmcnt(5)
	v_mfma_f32_32x32x16_bf16 v[16:31], v[148:151], v[152:155], v[16:31]
	v_sub_f32_e32 v34, v34, v212
	v_sub_f32_e32 v35, v35, v212
	v_sub_f32_e32 v36, v36, v212
	v_sub_f32_e32 v37, v37, v212
	v_sub_f32_e32 v38, v38, v212
	v_sub_f32_e32 v39, v39, v212
	v_exp_f32_e32 v32, v32
	s_waitcnt lgkmcnt(4)
	v_mfma_f32_32x32x16_bf16 v[0:15], v[144:147], v[152:155], v[0:15]
	v_exp_f32_e32 v33, v33
	v_exp_f32_e32 v34, v34
	v_exp_f32_e32 v35, v35
	v_exp_f32_e32 v36, v36
	v_exp_f32_e32 v37, v37
	v_exp_f32_e32 v38, v38
	v_exp_f32_e32 v39, v39
	v_cvt_pk_bf16_f32 v144, v32, v33
	v_cvt_pk_bf16_f32 v145, v34, v35
	v_cvt_pk_bf16_f32 v146, v36, v37
	v_cvt_pk_bf16_f32 v147, v38, v39
	v_sub_f32_e32 v40, v40, v212
	v_sub_f32_e32 v41, v41, v212
	s_waitcnt lgkmcnt(3)
	v_mfma_f32_32x32x16_bf16 v[16:31], v[140:143], v[144:147], v[16:31]
	v_sub_f32_e32 v42, v42, v212
	v_sub_f32_e32 v43, v43, v212
	v_sub_f32_e32 v44, v44, v212
	v_sub_f32_e32 v45, v45, v212
	v_sub_f32_e32 v46, v46, v212
	v_sub_f32_e32 v47, v47, v212
	v_exp_f32_e32 v40, v40
	s_waitcnt lgkmcnt(2)
	v_mfma_f32_32x32x16_bf16 v[0:15], v[136:139], v[144:147], v[0:15]
	v_exp_f32_e32 v41, v41
	v_exp_f32_e32 v42, v42
	v_exp_f32_e32 v43, v43
	v_exp_f32_e32 v44, v44
	v_exp_f32_e32 v45, v45
	v_exp_f32_e32 v46, v46
	v_exp_f32_e32 v47, v47
	v_cvt_pk_bf16_f32 v136, v40, v41
	v_cvt_pk_bf16_f32 v137, v42, v43
	v_cvt_pk_bf16_f32 v138, v44, v45
	v_cvt_pk_bf16_f32 v139, v46, v47
	s_waitcnt lgkmcnt(1)
	v_mfma_f32_32x32x16_bf16 v[16:31], v[132:135], v[136:139], v[16:31]
	s_waitcnt lgkmcnt(0)
	v_mfma_f32_32x32x16_bf16 v[0:15], v[128:131], v[136:139], v[0:15]
